# GEMM units that follow an epilogue run their first two super-phases with counted waits that leave the epilogue stores in flight (SwiGLU: 8 stores, store epilogue: counted 8/16)
# baseline (speedup 1.0000x reference)
; #define GETLANE() int lane; asm volatile("v_mbcnt_lo_u32_b32 %0, -1, 0\n\tv_mbcnt_hi_u32_b32 %0, -1, %0" : "=v"(lane)); const int tid = wave * 64 + lane
; __global__ void __launch_bounds__(NTHR) fwd_megakernel(Args a_unused) {
;     ...
;             else if (j == 4 || j == 6) {
;                 const int ng = j == 4 ? 1 : 2;
;                 for (int q = 0; q < ng; ++q) {
;                     GETLANE(); (void)lane;
;                     const bf16_t* A; const bf16_t* Bt; bf16_t* O; int N, K, ldc;
;                     if (j == 4) { A = XN; Bt = (const bf16_t*)(wb + W_IN); O = (bf16_t*)(ws + OFF_Z); N = 2048; K = D; ldc = INW; }
;                     else if (q == 0) { A = (const bf16_t*)(ws + OFF_CQN); Bt = (const bf16_t*)(wb + W_UQ); O = (bf16_t*)(ws + OFF_QRAW); N = 768; K = 256; ldc = 576; }
;                     else { A = (const bf16_t*)(ws + OFF_CKVN); Bt = (const bf16_t*)(wb + W_UKV); O = (bf16_t*)(ws + OFF_KVRAW); N = 768; K = 256; ldc = 768; }
;                     pg8::Gemm g{A, Bt, MTOT, N, K}; CtxOrder S; S.init(N, K, G, bid, 4, 1);
;                     EpiStore E{O, ldc, ldc}; pg8::gemm_phase<EpiStore, CtxOrder, true, true>(lds, g, S, E, tid);
.LBB0_958:
	s_mov_b32 s91, 0
	s_andn2_b64 vcc, exec, s[0:1]
	v_mbcnt_lo_u32_b32 v16, -1, 0
	v_mbcnt_hi_u32_b32 v16, -1, v16
	s_cbranch_vccnz .LBB0_960
	s_and_b64 s[20:21], s[14:15], exec
	s_movk_i32 s16, 0x240
	s_cselect_b32 s53, s16, 0x300
	s_mov_b32 s16, 0x11cd0000
	s_cselect_b32 s16, s16, 0x141f0000
	s_add_u32 s20, s10, s16
	s_addc_u32 s21, s11, 0
	s_and_b64 s[26:27], s[14:15], exec
	s_mov_b32 s16, 0x3900000
	s_cselect_b32 s16, s16, 0x3960000
	s_add_u32 s26, s10, s16
	s_addc_u32 s27, s11, 0
	s_and_b64 s[28:29], s[14:15], exec
	s_cselect_b32 s16, 0xfbd0000, s73
	s_add_u32 s28, s10, s16
	s_addc_u32 s29, s11, 0
	s_mov_b32 s54, 3
	s_movk_i32 s44, 0x100
	s_branch .LBB0_961

; #define PG8_STAGE(bufoff, gbase, voff) do { _Pragma("unroll") for (int _i = 0; _i < 2; ++_i) \
;         __builtin_amdgcn_global_load_lds((const unsigned*)((const char*)(gbase) + (voff)[_i]), (PG8_LAS unsigned*)(lds + (bufoff) + ldsw + _i * 8192), 16, 0, 0); } while (0)
; #define PG8_LDA(dst, b, h) do { _Pragma("unroll") for (int m = 0; m < 4; ++m) _Pragma("unroll") for (int k = 0; k < 2; ++k) dst[m][k] = *(const PG8_LAS bf16x8*)(lds + PG8_SA(b, h) + aoff + m * 2048 + k * 1024); } while (0)
; #define PG8_LDB(dst, b, h) do { _Pragma("unroll") for (int n = 0; n < 2; ++n) _Pragma("unroll") for (int k = 0; k < 2; ++k) dst[n][k] = *(const PG8_LAS bf16x8*)(lds + PG8_SB(b, h) + boff + n * 2048 + k * 1024); } while (0)
; #define PG8_WAIT_V(n) asm volatile("s_waitcnt vmcnt(" #n ")" ::: "memory")
; #define PG8_WAIT_L(n) asm volatile("s_waitcnt lgkmcnt(" #n ")" ::: "memory")
; #define PG8_BAR __builtin_amdgcn_s_barrier()
; #define PG8_SCHED __builtin_amdgcn_sched_barrier(0)
; template <class Epi, class Sched, bool ALIGN_EPI = false, bool SP2 = false>
; __device__ __forceinline__ void gemm_phase(PG8_LAS unsigned char* lds, const Gemm g, const Sched& S, const Epi& E, const int tid_in) {
;     ...
;             PG8_LDB(B0, 0, 0); PG8_LDB(B1, 0, 1); PG8_SCHED; PG8_LDA(At, 0, 0); PG8_STAGE(PG8_SA(1, 1), a1 + hstep, voffA);
;             PG8_WAIT_V(8); PG8_WAIT_L(0); PG8_BAR; PG8_MMA(0, 0, At, B0); PG8_MMA(0, 1, At, B1); PG8_BAR; PG8_SCHED;
;     ...
; #pragma unroll
;         for (int a = 0; a < 2; ++a)
; #pragma unroll
;             for (int b = 0; b < 2; ++b)
; #pragma unroll
;                 for (int m = 0; m < 4; ++m)
; #pragma unroll
;                     for (int n = 0; n < 2; ++n) acc[a][b][m][n] = (f32x4){0.f, 0.f, 0.f, 0.f};
;         cur = nxt; cA = nA; cB = nB; ++ui;
.LBB0_980:
	s_add_i32 s94, s93, -2
	s_add_u32 s40, s40, 0x80
	s_addc_u32 s41, s41, 0
	s_add_u32 s95, s48, 0x100
	v_mov_b32_e32 v2, 0
	s_addc_u32 s96, s49, 0
	s_mov_b32 s48, 0
	v_mov_b32_e32 v3, v2
	v_mov_b32_e32 v4, v2
	v_mov_b32_e32 v5, v2
	v_mov_b32_e32 v6, v2
	v_mov_b32_e32 v7, v2
	v_mov_b32_e32 v8, v2
	v_mov_b32_e32 v9, v2
	v_mov_b32_e32 v18, v2
	v_mov_b32_e32 v19, v2
	v_mov_b32_e32 v20, v2
	v_mov_b32_e32 v21, v2
	v_mov_b32_e32 v22, v2
	v_mov_b32_e32 v23, v2
	v_mov_b32_e32 v24, v2
	v_mov_b32_e32 v25, v2
	v_mov_b32_e32 v34, v2
	v_mov_b32_e32 v35, v2
	v_mov_b32_e32 v36, v2
	v_mov_b32_e32 v37, v2
	v_mov_b32_e32 v38, v2
	v_mov_b32_e32 v39, v2
	v_mov_b32_e32 v40, v2
	v_mov_b32_e32 v41, v2
	v_mov_b32_e32 v50, v2
	v_mov_b32_e32 v51, v2
	v_mov_b32_e32 v52, v2
	v_mov_b32_e32 v53, v2
	v_mov_b32_e32 v54, v2
	v_mov_b32_e32 v55, v2
	v_mov_b32_e32 v56, v2
	v_mov_b32_e32 v57, v2
	v_mov_b32_e32 v10, v2
	v_mov_b32_e32 v11, v2
	v_mov_b32_e32 v12, v2
	v_mov_b32_e32 v13, v2
	v_mov_b32_e32 v14, v2
	v_mov_b32_e32 v15, v2
	v_mov_b32_e32 v16, v2
	v_mov_b32_e32 v17, v2
	v_mov_b32_e32 v26, v2
	v_mov_b32_e32 v27, v2
	v_mov_b32_e32 v28, v2
	v_mov_b32_e32 v29, v2
	v_mov_b32_e32 v30, v2
	v_mov_b32_e32 v31, v2
	v_mov_b32_e32 v32, v2
	v_mov_b32_e32 v33, v2
	v_mov_b32_e32 v42, v2
	v_mov_b32_e32 v43, v2
	v_mov_b32_e32 v44, v2
	v_mov_b32_e32 v45, v2
	v_mov_b32_e32 v46, v2
	v_mov_b32_e32 v47, v2
	v_mov_b32_e32 v48, v2
	v_mov_b32_e32 v49, v2
	v_mov_b32_e32 v58, v2
	v_mov_b32_e32 v59, v2
	v_mov_b32_e32 v60, v2
	v_mov_b32_e32 v61, v2
	v_mov_b32_e32 v62, v2
	v_mov_b32_e32 v63, v2
	v_mov_b32_e32 v64, v2
	v_mov_b32_e32 v65, v2
	v_mov_b32_e32 v66, v2
	v_mov_b32_e32 v67, v2
	v_mov_b32_e32 v68, v2
	v_mov_b32_e32 v69, v2
	v_mov_b32_e32 v70, v2
	v_mov_b32_e32 v71, v2
	v_mov_b32_e32 v72, v2
	v_mov_b32_e32 v73, v2
	v_mov_b32_e32 v82, v2
	v_mov_b32_e32 v83, v2
	v_mov_b32_e32 v84, v2
	v_mov_b32_e32 v85, v2
	v_mov_b32_e32 v86, v2
	v_mov_b32_e32 v87, v2
	v_mov_b32_e32 v88, v2
	v_mov_b32_e32 v89, v2
	v_mov_b32_e32 v98, v2
	v_mov_b32_e32 v99, v2
	v_mov_b32_e32 v100, v2
	v_mov_b32_e32 v101, v2
	v_mov_b32_e32 v102, v2
	v_mov_b32_e32 v103, v2
	v_mov_b32_e32 v104, v2
	v_mov_b32_e32 v105, v2
	v_mov_b32_e32 v114, v2
	v_mov_b32_e32 v115, v2
	v_mov_b32_e32 v116, v2
	v_mov_b32_e32 v117, v2
	v_mov_b32_e32 v118, v2
	v_mov_b32_e32 v119, v2
	v_mov_b32_e32 v120, v2
	v_mov_b32_e32 v121, v2
	v_mov_b32_e32 v74, v2
	v_mov_b32_e32 v75, v2
	v_mov_b32_e32 v76, v2
	v_mov_b32_e32 v77, v2
	v_mov_b32_e32 v78, v2
	v_mov_b32_e32 v79, v2
	v_mov_b32_e32 v80, v2
	v_mov_b32_e32 v81, v2
	v_mov_b32_e32 v90, v2
	v_mov_b32_e32 v91, v2
	v_mov_b32_e32 v92, v2
	v_mov_b32_e32 v93, v2
	v_mov_b32_e32 v94, v2
	v_mov_b32_e32 v95, v2
	v_mov_b32_e32 v96, v2
	v_mov_b32_e32 v97, v2
	v_mov_b32_e32 v106, v2
	v_mov_b32_e32 v107, v2
	v_mov_b32_e32 v108, v2
	v_mov_b32_e32 v109, v2
	v_mov_b32_e32 v110, v2
	v_mov_b32_e32 v111, v2
	v_mov_b32_e32 v112, v2
	v_mov_b32_e32 v113, v2
	v_mov_b32_e32 v122, v2
	v_mov_b32_e32 v123, v2
	v_mov_b32_e32 v124, v2
	v_mov_b32_e32 v125, v2
	v_mov_b32_e32 v126, v2
	v_mov_b32_e32 v127, v2
	v_mov_b32_e32 v128, v2
	v_mov_b32_e32 v129, v2
	s_cmp_eq_u32 s91, 0
	s_cbranch_scc1 .LBB0_981
	s_add_i32 s97, s48, 2
	s_add_u32 vcc_lo, s40, 0x80
	s_addc_u32 s49, s41, 0
	s_add_i32 s87, 0, 0x10000
	s_cmp_eq_u32 s94, s48
	s_cselect_b32 s49, s45, s49
	s_cselect_b32 s48, s44, vcc_lo
	v_add_u32_e32 v149, s87, v147
	s_cselect_b32 vcc_hi, s47, s96
	s_cselect_b32 vcc_lo, s46, s95
	s_add_i32 s18, 0, 0x14000
	ds_read_b128 v[142:145], v149
	ds_read_b128 v[150:153], v149 offset:1024
	ds_read_b128 v[154:157], v149 offset:2048
	ds_read_b128 v[158:161], v149 offset:3072
	v_add_u32_e32 v149, s18, v147
	ds_read_b128 v[162:165], v149
	ds_read_b128 v[166:169], v149 offset:1024
	ds_read_b128 v[170:173], v149 offset:2048
	ds_read_b128 v[174:177], v149 offset:3072
	v_lshl_add_u64 v[218:219], s[40:41], 0, v[138:139]
	s_add_i32 m0, s59, 0xc000
	ds_read_b128 v[178:181], v148
	ds_read_b128 v[182:185], v148 offset:1024
	ds_read_b128 v[186:189], v148 offset:2048
	ds_read_b128 v[192:195], v148 offset:3072
	ds_read_b128 v[196:199], v148 offset:4096
	ds_read_b128 v[200:203], v148 offset:5120
	ds_read_b128 v[230:233], v148 offset:6144
	ds_read_b128 v[234:237], v148 offset:7168
	global_load_lds_dwordx4 v[218:219], off
	v_lshl_add_u64 v[218:219], s[40:41], 0, v[140:141]
	s_add_i32 m0, s59, 0xe000
	s_nop 0
	global_load_lds_dwordx4 v[218:219], off
	s_cmp_eq_u32 s91, 16
	s_cbranch_scc1 .Lpw0_24
	s_cmp_eq_u32 s91, 8
	s_cbranch_scc1 .Lpw0_16
	s_waitcnt vmcnt(8)
	s_branch .Lpw0_j
; #define PG8_STAGE(bufoff, gbase, voff) do { _Pragma("unroll") for (int _i = 0; _i < 2; ++_i) \
;         __builtin_amdgcn_global_load_lds((const unsigned*)((const char*)(gbase) + (voff)[_i]), (PG8_LAS unsigned*)(lds + (bufoff) + ldsw + _i * 8192), 16, 0, 0); } while (0)
; #define PG8_LDA(dst, b, h) do { _Pragma("unroll") for (int m = 0; m < 4; ++m) _Pragma("unroll") for (int k = 0; k < 2; ++k) dst[m][k] = *(const PG8_LAS bf16x8*)(lds + PG8_SA(b, h) + aoff + m * 2048 + k * 1024); } while (0)
; #define PG8_WAIT_V(n) asm volatile("s_waitcnt vmcnt(" #n ")" ::: "memory")
; #define PG8_WAIT_L(n) asm volatile("s_waitcnt lgkmcnt(" #n ")" ::: "memory")
; #define PG8_BAR __builtin_amdgcn_s_barrier()
; #define PG8_SCHED __builtin_amdgcn_sched_barrier(0)
; template <class Epi, class Sched, bool ALIGN_EPI = false, bool SP2 = false>
; __device__ __forceinline__ void gemm_phase(PG8_LAS unsigned char* lds, const Gemm g, const Sched& S, const Epi& E, const int tid_in) {
;     ...
;             PG8_WAIT_V(8); PG8_WAIT_L(0); PG8_BAR; PG8_MMA(0, 0, At, B0); PG8_MMA(0, 1, At, B1); PG8_BAR; PG8_SCHED;
;             PG8_LDA(At, 0, 1); PG8_STAGE(PG8_SB(0, 0), b2, voffB); PG8_STAGE(PG8_SB(0, 1), b2 + hstep, voffB); PG8_STAGE(PG8_SA(0, 0), a2, voffA);
;             PG8_WAIT_V(8); PG8_WAIT_L(0); PG8_BAR; PG8_MMA(1, 0, At, B0); PG8_MMA(1, 1, At, B1); PG8_BAR; PG8_SCHED;
.Lpw0_16:
	s_waitcnt vmcnt(16)
	s_branch .Lpw0_j
.Lpw0_24:
	s_waitcnt vmcnt(24)
.Lpw0_j:
	s_waitcnt lgkmcnt(0)
	s_barrier
	s_setprio 1
	s_waitcnt lgkmcnt(0)
	v_mfma_f32_16x16x32_f16 v[126:129], v[142:145], v[178:181], v[126:129]
	v_mfma_f32_16x16x32_f16 v[122:125], v[154:157], v[178:181], v[122:125]
	v_mfma_f32_16x16x32_f16 v[110:113], v[142:145], v[186:189], v[110:113]
	v_mfma_f32_16x16x32_f16 v[106:109], v[154:157], v[186:189], v[106:109]
	v_mfma_f32_16x16x32_f16 v[94:97], v[142:145], v[196:199], v[94:97]
	v_mfma_f32_16x16x32_f16 v[90:93], v[154:157], v[196:199], v[90:93]
	v_mfma_f32_16x16x32_f16 v[78:81], v[142:145], v[230:233], v[78:81]
	v_mfma_f32_16x16x32_f16 v[74:77], v[154:157], v[230:233], v[74:77]
	v_mfma_f32_16x16x32_f16 v[126:129], v[150:153], v[182:185], v[126:129]
	v_mfma_f32_16x16x32_f16 v[122:125], v[158:161], v[182:185], v[122:125]
	v_mfma_f32_16x16x32_f16 v[110:113], v[150:153], v[192:195], v[110:113]
	v_mfma_f32_16x16x32_f16 v[106:109], v[158:161], v[192:195], v[106:109]
	v_mfma_f32_16x16x32_f16 v[94:97], v[150:153], v[200:203], v[94:97]
	v_mfma_f32_16x16x32_f16 v[90:93], v[158:161], v[200:203], v[90:93]
	v_mfma_f32_16x16x32_f16 v[78:81], v[150:153], v[234:237], v[78:81]
	v_mfma_f32_16x16x32_f16 v[74:77], v[158:161], v[234:237], v[74:77]
	s_setprio 0
	s_setprio 1
	v_mfma_f32_16x16x32_f16 v[118:121], v[162:165], v[178:181], v[118:121]
	v_mfma_f32_16x16x32_f16 v[114:117], v[170:173], v[178:181], v[114:117]
	v_mfma_f32_16x16x32_f16 v[102:105], v[162:165], v[186:189], v[102:105]
	v_mfma_f32_16x16x32_f16 v[98:101], v[170:173], v[186:189], v[98:101]
	v_mfma_f32_16x16x32_f16 v[86:89], v[162:165], v[196:199], v[86:89]
	v_mfma_f32_16x16x32_f16 v[82:85], v[170:173], v[196:199], v[82:85]
	v_mfma_f32_16x16x32_f16 v[70:73], v[162:165], v[230:233], v[70:73]
	v_mfma_f32_16x16x32_f16 v[66:69], v[170:173], v[230:233], v[66:69]
	v_mfma_f32_16x16x32_f16 v[118:121], v[166:169], v[182:185], v[118:121]
	v_mfma_f32_16x16x32_f16 v[114:117], v[174:177], v[182:185], v[114:117]
	v_mfma_f32_16x16x32_f16 v[102:105], v[166:169], v[192:195], v[102:105]
	v_mfma_f32_16x16x32_f16 v[98:101], v[174:177], v[192:195], v[98:101]
	v_mfma_f32_16x16x32_f16 v[86:89], v[166:169], v[200:203], v[86:89]
	v_mfma_f32_16x16x32_f16 v[82:85], v[174:177], v[200:203], v[82:85]
	v_mfma_f32_16x16x32_f16 v[70:73], v[166:169], v[234:237], v[70:73]
	v_mfma_f32_16x16x32_f16 v[66:69], v[174:177], v[234:237], v[66:69]
	s_setprio 0
	s_barrier
	s_add_i32 s19, s87, s58
	v_lshl_add_u64 v[218:219], vcc, 0, v[132:133]
	s_mov_b32 m0, s19
	ds_read_b128 v[178:181], v148 offset:16384
	ds_read_b128 v[182:185], v148 offset:17408
	ds_read_b128 v[186:189], v148 offset:18432
	ds_read_b128 v[192:195], v148 offset:19456
	ds_read_b128 v[196:199], v148 offset:20480
	ds_read_b128 v[200:203], v148 offset:21504
	ds_read_b128 v[230:233], v148 offset:22528
	ds_read_b128 v[234:237], v148 offset:23552
	global_load_lds_dwordx4 v[218:219], off
	s_add_i32 m0, s19, 0x2000
	v_lshl_add_u64 v[220:221], vcc, 0, v[136:137]
	s_add_u32 vcc_lo, vcc_lo, s16
	s_addc_u32 vcc_hi, vcc_hi, 0
	s_add_i32 s18, s18, s58
	global_load_lds_dwordx4 v[220:221], off
	v_lshl_add_u64 v[222:223], vcc, 0, v[132:133]
	s_mov_b32 m0, s18
	v_lshl_add_u64 v[224:225], vcc, 0, v[136:137]
	global_load_lds_dwordx4 v[222:223], off
	s_add_i32 m0, s18, 0x2000
	v_lshl_add_u64 v[238:239], s[48:49], 0, v[130:131]
	global_load_lds_dwordx4 v[224:225], off
	s_mov_b32 m0, s59
	v_lshl_add_u64 v[240:241], s[48:49], 0, v[134:135]
	global_load_lds_dwordx4 v[238:239], off
	s_mov_b32 m0, s60
	s_nop 0
	global_load_lds_dwordx4 v[240:241], off
	s_cmp_eq_u32 s91, 16
	s_cbranch_scc1 .Lpw1_24
	s_cmp_eq_u32 s91, 8
	s_cbranch_scc1 .Lpw1_16
	s_waitcnt vmcnt(8)
	s_branch .Lpw1_j

; #define PG8_WAIT_V(n) asm volatile("s_waitcnt vmcnt(" #n ")" ::: "memory")
; #define PG8_WAIT_L(n) asm volatile("s_waitcnt lgkmcnt(" #n ")" ::: "memory")
; #define PG8_BAR __builtin_amdgcn_s_barrier()
; #define PG8_SCHED __builtin_amdgcn_sched_barrier(0)
; template <class Epi, class Sched, bool ALIGN_EPI = false, bool SP2 = false>
; __device__ __forceinline__ void gemm_phase(PG8_LAS unsigned char* lds, const Gemm g, const Sched& S, const Epi& E, const int tid_in) {
;     ...
;             PG8_WAIT_V(8); PG8_WAIT_L(0); PG8_BAR; PG8_MMA(1, 0, At, B0); PG8_MMA(1, 1, At, B1); PG8_BAR; PG8_SCHED;
.Lpw1_j:
	s_waitcnt lgkmcnt(0)
	s_barrier
	s_setprio 1
	s_waitcnt lgkmcnt(0)
	v_mfma_f32_16x16x32_f16 v[62:65], v[142:145], v[178:181], v[62:65]
	v_mfma_f32_16x16x32_f16 v[58:61], v[154:157], v[178:181], v[58:61]
	v_mfma_f32_16x16x32_f16 v[46:49], v[142:145], v[186:189], v[46:49]
	v_mfma_f32_16x16x32_f16 v[42:45], v[154:157], v[186:189], v[42:45]
	v_mfma_f32_16x16x32_f16 v[30:33], v[142:145], v[196:199], v[30:33]
	v_mfma_f32_16x16x32_f16 v[26:29], v[154:157], v[196:199], v[26:29]
	v_mfma_f32_16x16x32_f16 v[14:17], v[142:145], v[230:233], v[14:17]
	v_mfma_f32_16x16x32_f16 v[10:13], v[154:157], v[230:233], v[10:13]
	v_mfma_f32_16x16x32_f16 v[62:65], v[150:153], v[182:185], v[62:65]
	v_mfma_f32_16x16x32_f16 v[58:61], v[158:161], v[182:185], v[58:61]
	v_mfma_f32_16x16x32_f16 v[46:49], v[150:153], v[192:195], v[46:49]
	v_mfma_f32_16x16x32_f16 v[42:45], v[158:161], v[192:195], v[42:45]
	v_mfma_f32_16x16x32_f16 v[30:33], v[150:153], v[200:203], v[30:33]
	v_mfma_f32_16x16x32_f16 v[26:29], v[158:161], v[200:203], v[26:29]
	v_mfma_f32_16x16x32_f16 v[14:17], v[150:153], v[234:237], v[14:17]
	v_mfma_f32_16x16x32_f16 v[10:13], v[158:161], v[234:237], v[10:13]
	s_setprio 0
	s_setprio 1
	v_mfma_f32_16x16x32_f16 v[54:57], v[162:165], v[178:181], v[54:57]
	v_mfma_f32_16x16x32_f16 v[50:53], v[170:173], v[178:181], v[50:53]
	v_mfma_f32_16x16x32_f16 v[38:41], v[162:165], v[186:189], v[38:41]
	v_mfma_f32_16x16x32_f16 v[34:37], v[170:173], v[186:189], v[34:37]
	v_mfma_f32_16x16x32_f16 v[22:25], v[162:165], v[196:199], v[22:25]
	v_mfma_f32_16x16x32_f16 v[18:21], v[170:173], v[196:199], v[18:21]
	v_mfma_f32_16x16x32_f16 v[6:9], v[162:165], v[230:233], v[6:9]
	v_mfma_f32_16x16x32_f16 v[2:5], v[170:173], v[230:233], v[2:5]
	v_mfma_f32_16x16x32_f16 v[54:57], v[166:169], v[182:185], v[54:57]
	v_mfma_f32_16x16x32_f16 v[50:53], v[174:177], v[182:185], v[50:53]
	v_mfma_f32_16x16x32_f16 v[38:41], v[166:169], v[192:195], v[38:41]
	v_mfma_f32_16x16x32_f16 v[34:37], v[174:177], v[192:195], v[34:37]
	v_mfma_f32_16x16x32_f16 v[22:25], v[166:169], v[200:203], v[22:25]
	v_mfma_f32_16x16x32_f16 v[18:21], v[174:177], v[200:203], v[18:21]
	v_mfma_f32_16x16x32_f16 v[6:9], v[166:169], v[234:237], v[6:9]
	v_mfma_f32_16x16x32_f16 v[2:5], v[174:177], v[234:237], v[2:5]
	s_setprio 0
	s_barrier
	s_branch .Lmid_981

; #define PG8_STAGE(bufoff, gbase, voff) do { _Pragma("unroll") for (int _i = 0; _i < 2; ++_i) \
;         __builtin_amdgcn_global_load_lds((const unsigned*)((const char*)(gbase) + (voff)[_i]), (PG8_LAS unsigned*)(lds + (bufoff) + ldsw + _i * 8192), 16, 0, 0); } while (0)
; #define PG8_LDA(dst, b, h) do { _Pragma("unroll") for (int m = 0; m < 4; ++m) _Pragma("unroll") for (int k = 0; k < 2; ++k) dst[m][k] = *(const PG8_LAS bf16x8*)(lds + PG8_SA(b, h) + aoff + m * 2048 + k * 1024); } while (0)
; #define PG8_LDB(dst, b, h) do { _Pragma("unroll") for (int n = 0; n < 2; ++n) _Pragma("unroll") for (int k = 0; k < 2; ++k) dst[n][k] = *(const PG8_LAS bf16x8*)(lds + PG8_SB(b, h) + boff + n * 2048 + k * 1024); } while (0)
; #define PG8_WAIT_V(n) asm volatile("s_waitcnt vmcnt(" #n ")" ::: "memory")
; #define PG8_WAIT_L(n) asm volatile("s_waitcnt lgkmcnt(" #n ")" ::: "memory")
; #define PG8_BAR __builtin_amdgcn_s_barrier()
; #define PG8_SCHED __builtin_amdgcn_sched_barrier(0)
; template <class Epi, class Sched, bool ALIGN_EPI = false, bool SP2 = false>
; __device__ __forceinline__ void gemm_phase(PG8_LAS unsigned char* lds, const Gemm g, const Sched& S, const Epi& E, const int tid_in) {
;     ...
;             PG8_LDB(B0, 1, 0); PG8_LDB(B1, 1, 1); PG8_SCHED; PG8_LDA(At, 1, 0); PG8_STAGE(PG8_SA(0, 1), a2 + hstep, voffA);
;             PG8_WAIT_V(8); PG8_WAIT_L(0); PG8_BAR; PG8_MMA(0, 0, At, B0); PG8_MMA(0, 1, At, B1); PG8_BAR; PG8_SCHED;
.Lmid_981:
	s_add_i32 s18, 0, 0x18000
	v_add_u32_e32 v149, s18, v147
	s_add_i32 s19, 0, 0x1c000
	ds_read_b128 v[142:145], v149
	ds_read_b128 v[150:153], v149 offset:1024
	ds_read_b128 v[154:157], v149 offset:2048
	ds_read_b128 v[158:161], v149 offset:3072
	v_add_u32_e32 v149, s19, v147
	ds_read_b128 v[162:165], v149
	ds_read_b128 v[166:169], v149 offset:1024
	ds_read_b128 v[170:173], v149 offset:2048
	ds_read_b128 v[174:177], v149 offset:3072
	s_add_u32 s48, s48, s16
	s_addc_u32 s49, s49, 0
	s_mov_b32 m0, s61
	v_lshl_add_u64 v[242:243], s[48:49], 0, v[130:131]
	ds_read_b128 v[178:181], v148 offset:32768
	ds_read_b128 v[182:185], v148 offset:33792
	ds_read_b128 v[186:189], v148 offset:34816
	ds_read_b128 v[192:195], v148 offset:35840
	ds_read_b128 v[196:199], v148 offset:36864
	ds_read_b128 v[200:203], v148 offset:37888
	ds_read_b128 v[230:233], v148 offset:38912
	ds_read_b128 v[234:237], v148 offset:39936
	global_load_lds_dwordx4 v[242:243], off
	v_lshl_add_u64 v[242:243], s[48:49], 0, v[134:135]
	s_mov_b32 m0, s62
	s_nop 0
	global_load_lds_dwordx4 v[242:243], off
	s_waitcnt vmcnt(8)
	s_waitcnt lgkmcnt(0)
	s_barrier
	s_setprio 1
	s_waitcnt lgkmcnt(0)
	v_mfma_f32_16x16x32_f16 v[126:129], v[142:145], v[178:181], v[126:129]
	v_mfma_f32_16x16x32_f16 v[122:125], v[154:157], v[178:181], v[122:125]
	v_mfma_f32_16x16x32_f16 v[110:113], v[142:145], v[186:189], v[110:113]
	v_mfma_f32_16x16x32_f16 v[106:109], v[154:157], v[186:189], v[106:109]
	v_mfma_f32_16x16x32_f16 v[94:97], v[142:145], v[196:199], v[94:97]
	v_mfma_f32_16x16x32_f16 v[90:93], v[154:157], v[196:199], v[90:93]
	v_mfma_f32_16x16x32_f16 v[78:81], v[142:145], v[230:233], v[78:81]
	v_mfma_f32_16x16x32_f16 v[74:77], v[154:157], v[230:233], v[74:77]
	v_mfma_f32_16x16x32_f16 v[126:129], v[150:153], v[182:185], v[126:129]
	v_mfma_f32_16x16x32_f16 v[122:125], v[158:161], v[182:185], v[122:125]
	v_mfma_f32_16x16x32_f16 v[110:113], v[150:153], v[192:195], v[110:113]
	v_mfma_f32_16x16x32_f16 v[106:109], v[158:161], v[192:195], v[106:109]
	v_mfma_f32_16x16x32_f16 v[94:97], v[150:153], v[200:203], v[94:97]
	v_mfma_f32_16x16x32_f16 v[90:93], v[158:161], v[200:203], v[90:93]
	v_mfma_f32_16x16x32_f16 v[78:81], v[150:153], v[234:237], v[78:81]
	v_mfma_f32_16x16x32_f16 v[74:77], v[158:161], v[234:237], v[74:77]
	s_setprio 0
	s_setprio 1
	v_mfma_f32_16x16x32_f16 v[118:121], v[162:165], v[178:181], v[118:121]
	v_mfma_f32_16x16x32_f16 v[114:117], v[170:173], v[178:181], v[114:117]
	v_mfma_f32_16x16x32_f16 v[102:105], v[162:165], v[186:189], v[102:105]
	v_mfma_f32_16x16x32_f16 v[98:101], v[170:173], v[186:189], v[98:101]
	v_mfma_f32_16x16x32_f16 v[86:89], v[162:165], v[196:199], v[86:89]
	v_mfma_f32_16x16x32_f16 v[82:85], v[170:173], v[196:199], v[82:85]
	v_mfma_f32_16x16x32_f16 v[70:73], v[162:165], v[230:233], v[70:73]
	v_mfma_f32_16x16x32_f16 v[66:69], v[170:173], v[230:233], v[66:69]
	v_mfma_f32_16x16x32_f16 v[118:121], v[166:169], v[182:185], v[118:121]
	v_mfma_f32_16x16x32_f16 v[114:117], v[174:177], v[182:185], v[114:117]
	v_mfma_f32_16x16x32_f16 v[102:105], v[166:169], v[192:195], v[102:105]
	v_mfma_f32_16x16x32_f16 v[98:101], v[174:177], v[192:195], v[98:101]
	v_mfma_f32_16x16x32_f16 v[86:89], v[166:169], v[200:203], v[86:89]
	v_mfma_f32_16x16x32_f16 v[82:85], v[174:177], v[200:203], v[82:85]
	v_mfma_f32_16x16x32_f16 v[70:73], v[166:169], v[234:237], v[70:73]
	v_mfma_f32_16x16x32_f16 v[66:69], v[174:177], v[234:237], v[66:69]
	s_setprio 0
	s_barrier
; #define PG8_STAGE(bufoff, gbase, voff) do { _Pragma("unroll") for (int _i = 0; _i < 2; ++_i) \
;         __builtin_amdgcn_global_load_lds((const unsigned*)((const char*)(gbase) + (voff)[_i]), (PG8_LAS unsigned*)(lds + (bufoff) + ldsw + _i * 8192), 16, 0, 0); } while (0)
; #define PG8_LDA(dst, b, h) do { _Pragma("unroll") for (int m = 0; m < 4; ++m) _Pragma("unroll") for (int k = 0; k < 2; ++k) dst[m][k] = *(const PG8_LAS bf16x8*)(lds + PG8_SA(b, h) + aoff + m * 2048 + k * 1024); } while (0)
; #define PG8_WAIT_V(n) asm volatile("s_waitcnt vmcnt(" #n ")" ::: "memory")
; #define PG8_WAIT_L(n) asm volatile("s_waitcnt lgkmcnt(" #n ")" ::: "memory")
; #define PG8_BAR __builtin_amdgcn_s_barrier()
; #define PG8_SCHED __builtin_amdgcn_sched_barrier(0)
; template <class Epi, class Sched, bool ALIGN_EPI = false, bool SP2 = false>
; __device__ __forceinline__ void gemm_phase(PG8_LAS unsigned char* lds, const Gemm g, const Sched& S, const Epi& E, const int tid_in) {
;     ...
;         for (int t = 0; t < nt; t += 2) {
;             const bool last = (t == nt - 2);
;             const char* a1 = cA + (size_t)(t + 1) * kstep;
;             const char* a2 = last ? nA : cA + (size_t)(t + 2) * kstep; const char* b2 = last ? nB : cB + (size_t)(t + 2) * kstep;
;     ...
;             PG8_LDA(At, 1, 1); PG8_STAGE(PG8_SB(1, 0), b3, voffB); PG8_STAGE(PG8_SB(1, 1), b3 + hstep, voffB); PG8_STAGE(PG8_SA(1, 0), a3, voffA);
;             PG8_WAIT_V(8); PG8_WAIT_L(0); PG8_BAR; PG8_MMA(1, 0, At, B0); PG8_MMA(1, 1, At, B1); PG8_BAR; PG8_SCHED;
	s_add_i32 s18, s18, s58
	v_lshl_add_u64 v[218:219], v[218:219], 0, s[24:25]
	s_mov_b32 m0, s18
	ds_read_b128 v[178:181], v148 offset:49152
	ds_read_b128 v[182:185], v148 offset:50176
	ds_read_b128 v[186:189], v148 offset:51200
	ds_read_b128 v[192:195], v148 offset:52224
	ds_read_b128 v[196:199], v148 offset:53248
	ds_read_b128 v[200:203], v148 offset:54272
	ds_read_b128 v[230:233], v148 offset:55296
	ds_read_b128 v[234:237], v148 offset:56320
	global_load_lds_dwordx4 v[218:219], off
	v_lshl_add_u64 v[218:219], v[220:221], 0, s[24:25]
	s_add_i32 m0, s18, 0x2000
	s_add_i32 s18, s19, s58
	global_load_lds_dwordx4 v[218:219], off
	v_lshl_add_u64 v[218:219], v[222:223], 0, s[24:25]
	s_mov_b32 m0, s18
	s_nop 0
	global_load_lds_dwordx4 v[218:219], off
	v_lshl_add_u64 v[218:219], v[224:225], 0, s[24:25]
	s_add_i32 m0, s18, 0x2000
	s_nop 0
	global_load_lds_dwordx4 v[218:219], off
	v_lshl_add_u64 v[218:219], v[238:239], 0, s[24:25]
	s_mov_b32 m0, s65
	s_nop 0
	global_load_lds_dwordx4 v[218:219], off
	v_lshl_add_u64 v[218:219], v[240:241], 0, s[24:25]
	s_mov_b32 m0, s66
	s_nop 0
	global_load_lds_dwordx4 v[218:219], off
	s_waitcnt vmcnt(8)
	s_waitcnt lgkmcnt(0)
	s_barrier
	s_setprio 1
	s_waitcnt lgkmcnt(0)
	v_mfma_f32_16x16x32_f16 v[62:65], v[142:145], v[178:181], v[62:65]
	v_mfma_f32_16x16x32_f16 v[58:61], v[154:157], v[178:181], v[58:61]
	v_mfma_f32_16x16x32_f16 v[46:49], v[142:145], v[186:189], v[46:49]
	v_mfma_f32_16x16x32_f16 v[42:45], v[154:157], v[186:189], v[42:45]
	v_mfma_f32_16x16x32_f16 v[30:33], v[142:145], v[196:199], v[30:33]
	v_mfma_f32_16x16x32_f16 v[26:29], v[154:157], v[196:199], v[26:29]
	v_mfma_f32_16x16x32_f16 v[14:17], v[142:145], v[230:233], v[14:17]
	v_mfma_f32_16x16x32_f16 v[10:13], v[154:157], v[230:233], v[10:13]
	v_mfma_f32_16x16x32_f16 v[62:65], v[150:153], v[182:185], v[62:65]
	v_mfma_f32_16x16x32_f16 v[58:61], v[158:161], v[182:185], v[58:61]
	v_mfma_f32_16x16x32_f16 v[46:49], v[150:153], v[192:195], v[46:49]
	v_mfma_f32_16x16x32_f16 v[42:45], v[158:161], v[192:195], v[42:45]
	v_mfma_f32_16x16x32_f16 v[30:33], v[150:153], v[200:203], v[30:33]
	v_mfma_f32_16x16x32_f16 v[26:29], v[158:161], v[200:203], v[26:29]
	v_mfma_f32_16x16x32_f16 v[14:17], v[150:153], v[234:237], v[14:17]
	v_mfma_f32_16x16x32_f16 v[10:13], v[158:161], v[234:237], v[10:13]
	s_setprio 0
	s_setprio 1
	v_mfma_f32_16x16x32_f16 v[54:57], v[162:165], v[178:181], v[54:57]
	v_mfma_f32_16x16x32_f16 v[50:53], v[170:173], v[178:181], v[50:53]
	v_mfma_f32_16x16x32_f16 v[38:41], v[162:165], v[186:189], v[38:41]
	v_mfma_f32_16x16x32_f16 v[34:37], v[170:173], v[186:189], v[34:37]
	v_mfma_f32_16x16x32_f16 v[22:25], v[162:165], v[196:199], v[22:25]
	v_mfma_f32_16x16x32_f16 v[18:21], v[170:173], v[196:199], v[18:21]
	v_mfma_f32_16x16x32_f16 v[6:9], v[162:165], v[230:233], v[6:9]
	v_mfma_f32_16x16x32_f16 v[2:5], v[170:173], v[230:233], v[2:5]
	v_mfma_f32_16x16x32_f16 v[54:57], v[166:169], v[182:185], v[54:57]
	v_mfma_f32_16x16x32_f16 v[50:53], v[174:177], v[182:185], v[50:53]
	v_mfma_f32_16x16x32_f16 v[38:41], v[166:169], v[192:195], v[38:41]
	v_mfma_f32_16x16x32_f16 v[34:37], v[174:177], v[192:195], v[34:37]
	v_mfma_f32_16x16x32_f16 v[22:25], v[166:169], v[200:203], v[22:25]
	v_mfma_f32_16x16x32_f16 v[18:21], v[174:177], v[200:203], v[18:21]
	v_mfma_f32_16x16x32_f16 v[6:9], v[166:169], v[234:237], v[6:9]
	v_mfma_f32_16x16x32_f16 v[2:5], v[174:177], v[234:237], v[2:5]
	s_setprio 0
	s_barrier
	s_add_u32 s40, s40, 0x100
	s_addc_u32 s41, s41, 0
	s_add_u32 s95, s95, 0x100
	s_addc_u32 s96, s96, 0
	s_cmp_ge_i32 s97, s93
	s_mov_b32 s48, s97
	s_cbranch_scc0 .LBB0_981
	s_and_b64 vcc, exec, s[42:43]
	s_cbranch_vccz .LBB0_984

;     __device__ __forceinline__ void operator()(const pg8::f32x4 (&acc)[2][2][4][2], const pg8::Unit& uu, int wr, int wc, int fr, int fq) const {
;         asm volatile("" : "+v"(fr), "+v"(fq));
;         const int upm = uu.pm & 0xffff, upn = uu.pn & 0xffff, unt = uu.pm >> 16; (void)unt;
;         const int row0 = upm * 256 + wr * 64 + fr, col0 = upn * 256 + wc * 32 + 8 * fq;
; #pragma unroll
;         for (int ai = 0; ai < 2; ++ai)
; #pragma unroll
;             for (int m = 0; m < 4; ++m) { bf16_t* rowp = O + (size_t)(row0 + ai * 128 + m * 16) * ldc;
; #pragma unroll
;                 for (int bj = 0; bj < 2; ++bj) { const int col = col0 + bj * 128;
;                     if (col < ncols) { const pg8::f32x4 v0 = acc[ai][bj][m][0], v1 = acc[ai][bj][m][1];
;                         u32x4 w; w.x = pg8::cvt_pk_bf16(v0[0], v0[1]); w.y = pg8::cvt_pk_bf16(v0[2], v0[3]); w.z = pg8::cvt_pk_bf16(v1[0], v1[1]); w.w = pg8::cvt_pk_bf16(v1[2], v1[3]);
;                         *(u32x4*)(rowp + col) = w; } } }
.LBB0_984:
	s_mov_b32 s91, 0
	s_lshl_b32 s18, s68, 8
	s_and_b32 s18, s18, 0xffff00
	v_mov_b32_e32 v142, v1
	v_mov_b32_e32 v143, v146
	s_add_i32 s18, s18, s63
	s_nop 0
	v_add_u32_e32 v149, s18, v142
	s_lshl_b32 s18, s67, 8
	s_and_b32 s18, s18, 0xffff00
	s_or_b32 s18, s18, s64
	v_lshl_add_u32 v142, v143, 3, s18
	v_mad_i64_i32 v[144:145], s[40:41], v149, s53, 0
	v_lshl_add_u64 v[144:145], v[144:145], 1, s[20:21]
	v_cmp_gt_i32_e32 vcc, s53, v142
	s_and_saveexec_b64 s[40:41], vcc
	s_cbranch_execz .LBB0_986
	v_ashrrev_i32_e32 v143, 31, v142
	v_cvt_pk_f16_f32 v126, v126, v127
	v_cvt_pk_f16_f32 v127, v128, v129
	v_cvt_pk_f16_f32 v128, v122, v123
	v_cvt_pk_f16_f32 v129, v124, v125
	v_lshl_add_u64 v[122:123], v[142:143], 1, v[144:145]
	global_store_dwordx4 v[122:123], v[126:129], off
	s_add_i32 s91, s91, 1
.LBB0_986:
	s_or_b64 exec, exec, s[40:41]
	v_cmp_gt_i32_e64 s[40:41], s77, v142
	s_and_saveexec_b64 s[48:49], s[40:41]
	s_cbranch_execz .LBB0_988
	v_ashrrev_i32_e32 v143, 31, v142
	v_cvt_pk_f16_f32 v118, v118, v119
	v_cvt_pk_f16_f32 v119, v120, v121
	v_cvt_pk_f16_f32 v120, v114, v115
	v_cvt_pk_f16_f32 v121, v116, v117
	v_lshl_add_u64 v[114:115], v[142:143], 1, v[144:145]
	global_store_dwordx4 v[114:115], v[118:121], off offset:256
	s_add_i32 s91, s91, 1
.LBB0_988:
	s_or_b64 exec, exec, s[48:49]
	v_add_u32_e32 v114, 16, v149
	v_mad_i64_i32 v[114:115], s[48:49], v114, s53, 0
	v_lshl_add_u64 v[114:115], v[114:115], 1, s[20:21]
	s_and_saveexec_b64 s[48:49], vcc
	s_cbranch_execz .LBB0_990
	v_ashrrev_i32_e32 v143, 31, v142
	v_cvt_pk_f16_f32 v110, v110, v111
	v_cvt_pk_f16_f32 v111, v112, v113
	v_cvt_pk_f16_f32 v112, v106, v107
	v_cvt_pk_f16_f32 v113, v108, v109
	v_lshl_add_u64 v[106:107], v[142:143], 1, v[114:115]
	global_store_dwordx4 v[106:107], v[110:113], off
	s_add_i32 s91, s91, 1
.LBB0_990:
	s_or_b64 exec, exec, s[48:49]
	s_and_saveexec_b64 s[48:49], s[40:41]
	s_cbranch_execz .LBB0_992
	v_ashrrev_i32_e32 v143, 31, v142
	v_cvt_pk_f16_f32 v102, v102, v103
	v_cvt_pk_f16_f32 v103, v104, v105
	v_cvt_pk_f16_f32 v104, v98, v99
	v_cvt_pk_f16_f32 v105, v100, v101
	v_lshl_add_u64 v[98:99], v[142:143], 1, v[114:115]
	global_store_dwordx4 v[98:99], v[102:105], off offset:256
	s_add_i32 s91, s91, 1
.LBB0_992:
	s_or_b64 exec, exec, s[48:49]
	v_add_u32_e32 v98, 32, v149
	v_mad_i64_i32 v[98:99], s[48:49], v98, s53, 0
	v_lshl_add_u64 v[98:99], v[98:99], 1, s[20:21]
	s_and_saveexec_b64 s[48:49], vcc
	s_cbranch_execz .LBB0_994
	v_ashrrev_i32_e32 v143, 31, v142
	v_cvt_pk_f16_f32 v94, v94, v95
	v_cvt_pk_f16_f32 v95, v96, v97
	v_cvt_pk_f16_f32 v96, v90, v91
	v_cvt_pk_f16_f32 v97, v92, v93
	v_lshl_add_u64 v[90:91], v[142:143], 1, v[98:99]
	global_store_dwordx4 v[90:91], v[94:97], off
	s_add_i32 s91, s91, 1
.LBB0_994:
	s_or_b64 exec, exec, s[48:49]
	s_and_saveexec_b64 s[48:49], s[40:41]
	s_cbranch_execz .LBB0_996
	v_ashrrev_i32_e32 v143, 31, v142
	v_cvt_pk_f16_f32 v86, v86, v87
	v_cvt_pk_f16_f32 v87, v88, v89
	v_cvt_pk_f16_f32 v88, v82, v83
	v_cvt_pk_f16_f32 v89, v84, v85
	v_lshl_add_u64 v[82:83], v[142:143], 1, v[98:99]
	global_store_dwordx4 v[82:83], v[86:89], off offset:256
	s_add_i32 s91, s91, 1
.LBB0_996:
	s_or_b64 exec, exec, s[48:49]
	v_add_u32_e32 v82, 48, v149
	v_mad_i64_i32 v[82:83], s[48:49], v82, s53, 0
	v_lshl_add_u64 v[82:83], v[82:83], 1, s[20:21]
	s_and_saveexec_b64 s[48:49], vcc
	s_cbranch_execz .LBB0_998
	v_ashrrev_i32_e32 v143, 31, v142
	v_cvt_pk_f16_f32 v78, v78, v79
	v_cvt_pk_f16_f32 v79, v80, v81
	v_cvt_pk_f16_f32 v80, v74, v75
	v_cvt_pk_f16_f32 v81, v76, v77
	v_lshl_add_u64 v[74:75], v[142:143], 1, v[82:83]
	global_store_dwordx4 v[74:75], v[78:81], off
	s_add_i32 s91, s91, 1
;     __device__ __forceinline__ void operator()(const pg8::f32x4 (&acc)[2][2][4][2], const pg8::Unit& uu, int wr, int wc, int fr, int fq) const {
;     ...
; #pragma unroll
;         for (int ai = 0; ai < 2; ++ai)
; #pragma unroll
;             for (int m = 0; m < 4; ++m) { bf16_t* rowp = O + (size_t)(row0 + ai * 128 + m * 16) * ldc;
; #pragma unroll
;                 for (int bj = 0; bj < 2; ++bj) { const int col = col0 + bj * 128;
;                     if (col < ncols) { const pg8::f32x4 v0 = acc[ai][bj][m][0], v1 = acc[ai][bj][m][1];
;                         u32x4 w; w.x = pg8::cvt_pk_bf16(v0[0], v0[1]); w.y = pg8::cvt_pk_bf16(v0[2], v0[3]); w.z = pg8::cvt_pk_bf16(v1[0], v1[1]); w.w = pg8::cvt_pk_bf16(v1[2], v1[3]);
;                         *(u32x4*)(rowp + col) = w; } } }
.LBB0_998:
	s_or_b64 exec, exec, s[48:49]
	s_and_saveexec_b64 s[48:49], s[40:41]
	s_cbranch_execz .LBB0_1000
	v_ashrrev_i32_e32 v143, 31, v142
	v_cvt_pk_f16_f32 v70, v70, v71
	v_cvt_pk_f16_f32 v71, v72, v73
	v_cvt_pk_f16_f32 v72, v66, v67
	v_cvt_pk_f16_f32 v73, v68, v69
	v_lshl_add_u64 v[66:67], v[142:143], 1, v[82:83]
	global_store_dwordx4 v[66:67], v[70:73], off offset:256
	s_add_i32 s91, s91, 1
.LBB0_1000:
	s_or_b64 exec, exec, s[48:49]
	v_add_u32_e32 v66, 0x80, v149
	v_mad_i64_i32 v[66:67], s[48:49], v66, s53, 0
	v_lshl_add_u64 v[66:67], v[66:67], 1, s[20:21]
	s_and_saveexec_b64 s[48:49], vcc
	s_cbranch_execz .LBB0_1002
	v_ashrrev_i32_e32 v143, 31, v142
	v_cvt_pk_f16_f32 v62, v62, v63
	v_cvt_pk_f16_f32 v63, v64, v65
	v_cvt_pk_f16_f32 v64, v58, v59
	v_cvt_pk_f16_f32 v65, v60, v61
	v_lshl_add_u64 v[58:59], v[142:143], 1, v[66:67]
	global_store_dwordx4 v[58:59], v[62:65], off
	s_add_i32 s91, s91, 1
.LBB0_1002:
	s_or_b64 exec, exec, s[48:49]
	s_and_saveexec_b64 s[48:49], s[40:41]
	s_cbranch_execz .LBB0_1004
	v_ashrrev_i32_e32 v143, 31, v142
	v_cvt_pk_f16_f32 v54, v54, v55
	v_cvt_pk_f16_f32 v55, v56, v57
	v_cvt_pk_f16_f32 v56, v50, v51
	v_cvt_pk_f16_f32 v57, v52, v53
	v_lshl_add_u64 v[50:51], v[142:143], 1, v[66:67]
	global_store_dwordx4 v[50:51], v[54:57], off offset:256
	s_add_i32 s91, s91, 1
.LBB0_1004:
	s_or_b64 exec, exec, s[48:49]
	v_add_u32_e32 v50, 0x90, v149
	v_mad_i64_i32 v[50:51], s[48:49], v50, s53, 0
	v_lshl_add_u64 v[50:51], v[50:51], 1, s[20:21]
	s_and_saveexec_b64 s[48:49], vcc
	s_cbranch_execz .LBB0_1006
	v_ashrrev_i32_e32 v143, 31, v142
	v_cvt_pk_f16_f32 v46, v46, v47
	v_cvt_pk_f16_f32 v47, v48, v49
	v_cvt_pk_f16_f32 v48, v42, v43
	v_cvt_pk_f16_f32 v49, v44, v45
	v_lshl_add_u64 v[42:43], v[142:143], 1, v[50:51]
	global_store_dwordx4 v[42:43], v[46:49], off
	s_add_i32 s91, s91, 1
.LBB0_1006:
	s_or_b64 exec, exec, s[48:49]
	s_and_saveexec_b64 s[48:49], s[40:41]
	s_cbranch_execz .LBB0_1008
	v_ashrrev_i32_e32 v143, 31, v142
	v_cvt_pk_f16_f32 v38, v38, v39
	v_cvt_pk_f16_f32 v39, v40, v41
	v_cvt_pk_f16_f32 v40, v34, v35
	v_cvt_pk_f16_f32 v41, v36, v37
	v_lshl_add_u64 v[34:35], v[142:143], 1, v[50:51]
	global_store_dwordx4 v[34:35], v[38:41], off offset:256
	s_add_i32 s91, s91, 1
.LBB0_1008:
	s_or_b64 exec, exec, s[48:49]
	v_add_u32_e32 v34, 0xa0, v149
	v_mad_i64_i32 v[34:35], s[48:49], v34, s53, 0
	v_lshl_add_u64 v[34:35], v[34:35], 1, s[20:21]
	s_and_saveexec_b64 s[48:49], vcc
	s_cbranch_execz .LBB0_1010
	v_ashrrev_i32_e32 v143, 31, v142
	v_cvt_pk_f16_f32 v30, v30, v31
	v_cvt_pk_f16_f32 v31, v32, v33
	v_cvt_pk_f16_f32 v32, v26, v27
	v_cvt_pk_f16_f32 v33, v28, v29
	v_lshl_add_u64 v[26:27], v[142:143], 1, v[34:35]
	global_store_dwordx4 v[26:27], v[30:33], off
	s_add_i32 s91, s91, 1
.LBB0_1010:
	s_or_b64 exec, exec, s[48:49]
	s_and_saveexec_b64 s[48:49], s[40:41]
	s_cbranch_execz .LBB0_1012
	v_ashrrev_i32_e32 v143, 31, v142
	v_cvt_pk_f16_f32 v22, v22, v23
	v_cvt_pk_f16_f32 v23, v24, v25
	v_cvt_pk_f16_f32 v24, v18, v19
	v_cvt_pk_f16_f32 v25, v20, v21
	v_lshl_add_u64 v[18:19], v[142:143], 1, v[34:35]
	global_store_dwordx4 v[18:19], v[22:25], off offset:256
	s_add_i32 s91, s91, 1
.LBB0_1012:
	s_or_b64 exec, exec, s[48:49]
	v_add_u32_e32 v18, 0xb0, v149
	v_mad_i64_i32 v[18:19], s[48:49], v18, s53, 0
	v_lshl_add_u64 v[18:19], v[18:19], 1, s[20:21]
	s_and_saveexec_b64 s[48:49], vcc
	s_cbranch_execz .LBB0_1018
	v_ashrrev_i32_e32 v143, 31, v142
	v_cvt_pk_f16_f32 v14, v14, v15
	v_cvt_pk_f16_f32 v15, v16, v17
	v_cvt_pk_f16_f32 v16, v10, v11
	v_cvt_pk_f16_f32 v17, v12, v13
	v_lshl_add_u64 v[10:11], v[142:143], 1, v[18:19]
	global_store_dwordx4 v[10:11], v[14:17], off
	s_add_i32 s91, s91, 1
	s_or_b64 exec, exec, s[48:49]
	s_and_saveexec_b64 s[48:49], s[40:41]
	s_cbranch_execnz .LBB0_1019

; #define PG8_BAR __builtin_amdgcn_s_barrier()
; template <class Epi, class Sched, bool ALIGN_EPI = false, bool SP2 = false>
; __device__ __forceinline__ void gemm_phase(PG8_LAS unsigned char* lds, const Gemm g, const Sched& S, const Epi& E, const int tid_in) {
;     ...
;         if (!has_next) break;
; #pragma unroll
;         for (int a = 0; a < 2; ++a)
; #pragma unroll
;             for (int b = 0; b < 2; ++b)
; #pragma unroll
;                 for (int m = 0; m < 4; ++m)
; #pragma unroll
;                     for (int n = 0; n < 2; ++n) acc[a][b][m][n] = (f32x4){0.f, 0.f, 0.f, 0.f};
;         cur = nxt; cA = nA; cB = nB; ++ui;
;         if constexpr (ALIGN_EPI) { if (wr == 1) PG8_BAR; }
;     }
;     __device__ __forceinline__ void operator()(const pg8::f32x4 (&acc)[2][2][4][2], const pg8::Unit& uu, int wr, int wc, int fr, int fq) const {
;     ...
;                 for (int bj = 0; bj < 2; ++bj) { const int col = col0 + bj * 128;
;                     if (col < ncols) { const pg8::f32x4 v0 = acc[ai][bj][m][0], v1 = acc[ai][bj][m][1];
;                         u32x4 w; w.x = pg8::cvt_pk_bf16(v0[0], v0[1]); w.y = pg8::cvt_pk_bf16(v0[2], v0[3]); w.z = pg8::cvt_pk_bf16(v1[0], v1[1]); w.w = pg8::cvt_pk_bf16(v1[2], v1[3]);
;                         *(u32x4*)(rowp + col) = w; } } }
.LBB0_1019:
	v_ashrrev_i32_e32 v143, 31, v142
	v_cvt_pk_f16_f32 v6, v6, v7
	v_cvt_pk_f16_f32 v7, v8, v9
	v_cvt_pk_f16_f32 v8, v2, v3
	v_cvt_pk_f16_f32 v9, v4, v5
	v_lshl_add_u64 v[2:3], v[142:143], 1, v[18:19]
	global_store_dwordx4 v[2:3], v[6:9], off offset:256
	s_add_i32 s91, s91, 1
	s_or_b64 exec, exec, s[48:49]
	s_and_b64 vcc, exec, s[38:39]
	s_mov_b64 s[38:39], -1
	s_cbranch_vccnz .LBB0_971
